# baseline (speedup 1.0000x reference)
; template <int EPI, int MB, int NB> ...
;     ...
;   } else if constexpr (EPI == EPI_AP) {
; #pragma unroll
;     for (int m = 0; m < MB; ++m) {
;       const size_t ob = (size_t)(brow + lrow0 + m * 16) * DM + col0;
;       u32x2 oo[2], gg[2];
;       unwiden16(*(const i32x4*)(e.sga + ob + wofs), gg[0], gg[1]);
; #pragma unroll
;       for (int n = 0; n < NB; ++n) {
;         const u32x2 g = gg[n];
;         oo[n][0] = pk_bf16(__uint_as_float(g[0] << 16) * acc[m][n][0], __uint_as_float(g[0] & 0xffff0000u) * acc[m][n][1]);
;         oo[n][1] = pk_bf16(__uint_as_float(g[1] << 16) * acc[m][n][2], __uint_as_float(g[1] & 0xffff0000u) * acc[m][n][3]);
;       }
;       *(i32x4*)(e.o16 + ob + wofs) = widen16(oo[0], oo[1]);
;     }
.LBB0_342:
	v_mov_b32_e32 v129, v231
	v_mov_b32_e32 v128, v232
	s_mov_b32 s35, s38
	v_add_u32_e32 v130, s40, v129
	v_add_u32_e32 v128, s42, v128
	v_ashrrev_i32_e32 v131, 31, v130
	v_ashrrev_i32_e32 v129, 31, v128
	v_lshlrev_b64 v[130:131], 11, v[130:131]
	v_lshl_add_u64 v[128:129], v[130:131], 0, v[128:129]
	v_lshlrev_b64 v[128:129], 1, v[128:129]
	v_lshl_add_u64 v[130:131], v[210:211], 0, v[128:129]
	v_mov_b32_e32 v162, 0x10000
	v_mov_b32_e32 v163, 0
	global_load_dwordx4 v[144:147], v[130:131], off
	v_lshl_add_u64 v[160:161], v[130:131], 0, v[162:163]
	global_load_dwordx4 v[148:151], v[160:161], off
	v_lshl_add_u64 v[160:161], v[160:161], 0, v[162:163]
	global_load_dwordx4 v[152:155], v[160:161], off
	v_lshl_add_u64 v[160:161], v[160:161], 0, v[162:163]
	global_load_dwordx4 v[156:159], v[160:161], off
	v_lshl_add_u64 v[134:135], v[212:213], 0, v[128:129]
	v_lshl_add_u64 v[136:137], v[128:129], 0, s[28:29]
	v_lshl_add_u64 v[138:139], v[210:211], 0, v[136:137]
	s_andn2_b64 vcc, exec, s[36:37]
	s_mov_b32 s39, s34
	s_waitcnt vmcnt(3)
	v_mov_b32_e32 v130, v144
	v_mov_b32_e32 v131, v145
	v_mov_b32_e32 v132, v146
	v_mov_b32_e32 v133, v147
	v_mov_b32_e32 v141, v132
	v_mov_b32_e32 v143, v133
	s_nop 0
	v_permlane16_swap_b32_e32 v130, v141
	v_permlane16_swap_b32_e32 v131, v143
	v_lshlrev_b32_e32 v132, 16, v130
	v_and_b32_e32 v133, 0xffff0000, v130
	v_lshlrev_b32_e32 v130, 16, v131
	v_and_b32_e32 v131, 0xffff0000, v131
	v_lshlrev_b32_e32 v140, 16, v141
	v_and_b32_e32 v141, 0xffff0000, v141
	v_lshlrev_b32_e32 v142, 16, v143
	v_and_b32_e32 v143, 0xffff0000, v143
	v_pk_mul_f32 v[120:121], v[120:121], v[132:133]
	v_pk_mul_f32 v[122:123], v[122:123], v[130:131]
	v_pk_mul_f32 v[124:125], v[124:125], v[140:141]
	v_pk_mul_f32 v[126:127], v[126:127], v[142:143]
	v_cvt_pk_bf16_f32 v120, v120, v121
	v_cvt_pk_bf16_f32 v121, v122, v123
	v_cvt_pk_bf16_f32 v122, v124, v125
	v_cvt_pk_bf16_f32 v123, v126, v127
	s_nop 0
	v_permlane16_swap_b32_e32 v120, v122
	v_permlane16_swap_b32_e32 v121, v123
	global_store_dwordx4 v[134:135], v[120:123], off
	v_lshl_add_u64 v[124:125], v[128:129], 0, s[4:5]
	v_lshl_add_u64 v[126:127], v[212:213], 0, v[136:137]
	v_lshl_add_u64 v[130:131], v[210:211], 0, v[124:125]
	s_waitcnt vmcnt(3)
	v_mov_b32_e32 v120, v148
	v_mov_b32_e32 v121, v149
	v_mov_b32_e32 v122, v150
	v_mov_b32_e32 v123, v151
	v_mov_b32_e32 v133, v122
	v_mov_b32_e32 v135, v123
	s_nop 0
	v_permlane16_swap_b32_e32 v120, v133
	v_permlane16_swap_b32_e32 v121, v135
	v_lshlrev_b32_e32 v122, 16, v120
	v_and_b32_e32 v123, 0xffff0000, v120
	v_lshlrev_b32_e32 v120, 16, v121
	v_and_b32_e32 v121, 0xffff0000, v121
	v_lshlrev_b32_e32 v132, 16, v133
	v_and_b32_e32 v133, 0xffff0000, v133
	v_lshlrev_b32_e32 v134, 16, v135
	v_and_b32_e32 v135, 0xffff0000, v135
	v_pk_mul_f32 v[112:113], v[112:113], v[122:123]
	v_pk_mul_f32 v[114:115], v[114:115], v[120:121]
	v_pk_mul_f32 v[116:117], v[116:117], v[132:133]
	v_pk_mul_f32 v[118:119], v[118:119], v[134:135]
	v_cvt_pk_bf16_f32 v112, v112, v113
	v_cvt_pk_bf16_f32 v113, v114, v115
	v_cvt_pk_bf16_f32 v114, v116, v117
	v_cvt_pk_bf16_f32 v115, v118, v119
	s_nop 0
	v_permlane16_swap_b32_e32 v112, v114
	v_permlane16_swap_b32_e32 v113, v115
	global_store_dwordx4 v[126:127], v[112:115], off
	v_lshl_add_u64 v[118:119], v[212:213], 0, v[124:125]
	v_lshl_add_u64 v[116:117], v[128:129], 0, s[30:31]
	v_lshl_add_u64 v[120:121], v[210:211], 0, v[116:117]
	s_waitcnt vmcnt(3)
	v_mov_b32_e32 v112, v152
	v_mov_b32_e32 v113, v153
	v_mov_b32_e32 v114, v154
	v_mov_b32_e32 v115, v155
	v_mov_b32_e32 v123, v114
	v_mov_b32_e32 v125, v115
	s_nop 0
	v_permlane16_swap_b32_e32 v112, v123
	v_permlane16_swap_b32_e32 v113, v125
	v_lshlrev_b32_e32 v114, 16, v112
	v_and_b32_e32 v115, 0xffff0000, v112
	v_lshlrev_b32_e32 v112, 16, v113
	v_and_b32_e32 v113, 0xffff0000, v113
	v_lshlrev_b32_e32 v122, 16, v123
	v_and_b32_e32 v123, 0xffff0000, v123
	v_lshlrev_b32_e32 v124, 16, v125
	v_and_b32_e32 v125, 0xffff0000, v125
	v_pk_mul_f32 v[104:105], v[104:105], v[114:115]
	v_pk_mul_f32 v[106:107], v[106:107], v[112:113]
	v_pk_mul_f32 v[108:109], v[108:109], v[122:123]
	v_pk_mul_f32 v[110:111], v[110:111], v[124:125]
	v_cvt_pk_bf16_f32 v104, v104, v105
	v_cvt_pk_bf16_f32 v105, v106, v107
	v_cvt_pk_bf16_f32 v106, v108, v109
	v_cvt_pk_bf16_f32 v107, v110, v111
	s_nop 0
	v_permlane16_swap_b32_e32 v104, v106
	v_permlane16_swap_b32_e32 v105, v107
	global_store_dwordx4 v[118:119], v[104:107], off
	v_mov_b32_e32 v114, v231
	v_mov_b32_e32 v115, v233
	v_lshl_add_u64 v[108:109], v[212:213], 0, v[116:117]
	s_waitcnt vmcnt(3)
	v_mov_b32_e32 v104, v156
	v_mov_b32_e32 v105, v157
	v_mov_b32_e32 v106, v158
	v_mov_b32_e32 v107, v159
	v_mov_b32_e32 v111, v106
	v_mov_b32_e32 v113, v107
	s_nop 0
	v_permlane16_swap_b32_e32 v104, v111
	v_permlane16_swap_b32_e32 v105, v113
	v_lshlrev_b32_e32 v106, 16, v104
	v_and_b32_e32 v107, 0xffff0000, v104
	v_lshlrev_b32_e32 v104, 16, v105
	v_and_b32_e32 v105, 0xffff0000, v105
	v_lshlrev_b32_e32 v110, 16, v111
	v_and_b32_e32 v111, 0xffff0000, v111
	v_lshlrev_b32_e32 v112, 16, v113
	v_and_b32_e32 v113, 0xffff0000, v113
	v_pk_mul_f32 v[96:97], v[96:97], v[106:107]
	v_pk_mul_f32 v[98:99], v[98:99], v[104:105]
	v_pk_mul_f32 v[100:101], v[100:101], v[110:111]
	v_pk_mul_f32 v[102:103], v[102:103], v[112:113]
	v_cvt_pk_bf16_f32 v96, v96, v97
	v_cvt_pk_bf16_f32 v97, v98, v99
	v_cvt_pk_bf16_f32 v98, v100, v101
	v_cvt_pk_bf16_f32 v99, v102, v103
	s_nop 0
	v_permlane16_swap_b32_e32 v96, v98
	v_permlane16_swap_b32_e32 v97, v99
	global_store_dwordx4 v[108:109], v[96:99], off
	s_nop 1
	v_add_u32_e32 v98, s40, v114
	v_add_u32_e32 v96, s42, v115
	v_ashrrev_i32_e32 v99, 31, v98
	v_ashrrev_i32_e32 v97, 31, v96
	v_lshlrev_b64 v[98:99], 11, v[98:99]
	v_lshl_add_u64 v[96:97], v[98:99], 0, v[96:97]
	v_lshlrev_b64 v[96:97], 1, v[96:97]
	v_lshl_add_u64 v[98:99], v[210:211], 0, v[96:97]
	v_mov_b32_e32 v162, 0x10000
	v_mov_b32_e32 v163, 0
	global_load_dwordx4 v[144:147], v[98:99], off
	v_lshl_add_u64 v[160:161], v[98:99], 0, v[162:163]
	global_load_dwordx4 v[148:151], v[160:161], off
	v_lshl_add_u64 v[160:161], v[160:161], 0, v[162:163]
	global_load_dwordx4 v[152:155], v[160:161], off
	v_lshl_add_u64 v[160:161], v[160:161], 0, v[162:163]
	global_load_dwordx4 v[156:159], v[160:161], off
	v_lshl_add_u64 v[102:103], v[212:213], 0, v[96:97]
	v_lshl_add_u64 v[104:105], v[96:97], 0, s[28:29]
	v_lshl_add_u64 v[106:107], v[210:211], 0, v[104:105]
	s_waitcnt vmcnt(3)
; template <int EPI, int MB, int NB> ...
;     ...
;   } else if constexpr (EPI == EPI_AP) {
; #pragma unroll
;     for (int m = 0; m < MB; ++m) {
;       const size_t ob = (size_t)(brow + lrow0 + m * 16) * DM + col0;
;       u32x2 oo[2], gg[2];
;       unwiden16(*(const i32x4*)(e.sga + ob + wofs), gg[0], gg[1]);
; #pragma unroll
;       for (int n = 0; n < NB; ++n) {
;         const u32x2 g = gg[n];
;         oo[n][0] = pk_bf16(__uint_as_float(g[0] << 16) * acc[m][n][0], __uint_as_float(g[0] & 0xffff0000u) * acc[m][n][1]);
;         oo[n][1] = pk_bf16(__uint_as_float(g[1] << 16) * acc[m][n][2], __uint_as_float(g[1] & 0xffff0000u) * acc[m][n][3]);
;       }
;       *(i32x4*)(e.o16 + ob + wofs) = widen16(oo[0], oo[1]);
;     }
	v_mov_b32_e32 v98, v144
	v_mov_b32_e32 v99, v145
	v_mov_b32_e32 v100, v146
	v_mov_b32_e32 v101, v147
	v_mov_b32_e32 v109, v100
	v_mov_b32_e32 v111, v101
	s_nop 0
	v_permlane16_swap_b32_e32 v98, v109
	v_permlane16_swap_b32_e32 v99, v111
	v_lshlrev_b32_e32 v100, 16, v98
	v_and_b32_e32 v101, 0xffff0000, v98
	v_lshlrev_b32_e32 v98, 16, v99
	v_and_b32_e32 v99, 0xffff0000, v99
	v_lshlrev_b32_e32 v108, 16, v109
	v_and_b32_e32 v109, 0xffff0000, v109
	v_lshlrev_b32_e32 v110, 16, v111
	v_and_b32_e32 v111, 0xffff0000, v111
	v_pk_mul_f32 v[88:89], v[88:89], v[100:101]
	v_pk_mul_f32 v[90:91], v[90:91], v[98:99]
	v_pk_mul_f32 v[92:93], v[92:93], v[108:109]
	v_pk_mul_f32 v[94:95], v[94:95], v[110:111]
	v_cvt_pk_bf16_f32 v88, v88, v89
	v_cvt_pk_bf16_f32 v89, v90, v91
	v_cvt_pk_bf16_f32 v90, v92, v93
	v_cvt_pk_bf16_f32 v91, v94, v95
	s_nop 0
	v_permlane16_swap_b32_e32 v88, v90
	v_permlane16_swap_b32_e32 v89, v91
	global_store_dwordx4 v[102:103], v[88:91], off
	v_lshl_add_u64 v[92:93], v[96:97], 0, s[4:5]
	v_lshl_add_u64 v[94:95], v[212:213], 0, v[104:105]
	v_lshl_add_u64 v[98:99], v[210:211], 0, v[92:93]
	s_waitcnt vmcnt(3)
	v_mov_b32_e32 v88, v148
	v_mov_b32_e32 v89, v149
	v_mov_b32_e32 v90, v150
	v_mov_b32_e32 v91, v151
	v_mov_b32_e32 v101, v90
	v_mov_b32_e32 v103, v91
	s_nop 0
	v_permlane16_swap_b32_e32 v88, v101
	v_permlane16_swap_b32_e32 v89, v103
	v_lshlrev_b32_e32 v90, 16, v88
	v_and_b32_e32 v91, 0xffff0000, v88
	v_lshlrev_b32_e32 v88, 16, v89
	v_and_b32_e32 v89, 0xffff0000, v89
	v_lshlrev_b32_e32 v100, 16, v101
	v_and_b32_e32 v101, 0xffff0000, v101
	v_lshlrev_b32_e32 v102, 16, v103
	v_and_b32_e32 v103, 0xffff0000, v103
	v_pk_mul_f32 v[80:81], v[80:81], v[90:91]
	v_pk_mul_f32 v[82:83], v[82:83], v[88:89]
	v_pk_mul_f32 v[84:85], v[84:85], v[100:101]
	v_pk_mul_f32 v[86:87], v[86:87], v[102:103]
	v_cvt_pk_bf16_f32 v80, v80, v81
	v_cvt_pk_bf16_f32 v81, v82, v83
	v_cvt_pk_bf16_f32 v82, v84, v85
	v_cvt_pk_bf16_f32 v83, v86, v87
	s_nop 0
	v_permlane16_swap_b32_e32 v80, v82
	v_permlane16_swap_b32_e32 v81, v83
	global_store_dwordx4 v[94:95], v[80:83], off
	v_lshl_add_u64 v[86:87], v[212:213], 0, v[92:93]
	v_lshl_add_u64 v[84:85], v[96:97], 0, s[30:31]
	v_lshl_add_u64 v[88:89], v[210:211], 0, v[84:85]
	s_waitcnt vmcnt(3)
	v_mov_b32_e32 v80, v152
	v_mov_b32_e32 v81, v153
	v_mov_b32_e32 v82, v154
	v_mov_b32_e32 v83, v155
	v_mov_b32_e32 v91, v82
	v_mov_b32_e32 v93, v83
	s_nop 0
	v_permlane16_swap_b32_e32 v80, v91
	v_permlane16_swap_b32_e32 v81, v93
	v_lshlrev_b32_e32 v82, 16, v80
	v_and_b32_e32 v83, 0xffff0000, v80
	v_lshlrev_b32_e32 v80, 16, v81
	v_and_b32_e32 v81, 0xffff0000, v81
	v_lshlrev_b32_e32 v90, 16, v91
	v_and_b32_e32 v91, 0xffff0000, v91
	v_lshlrev_b32_e32 v92, 16, v93
	v_and_b32_e32 v93, 0xffff0000, v93
	v_pk_mul_f32 v[72:73], v[72:73], v[82:83]
	v_pk_mul_f32 v[74:75], v[74:75], v[80:81]
	v_pk_mul_f32 v[76:77], v[76:77], v[90:91]
	v_pk_mul_f32 v[78:79], v[78:79], v[92:93]
	v_cvt_pk_bf16_f32 v72, v72, v73
	v_cvt_pk_bf16_f32 v73, v74, v75
	v_cvt_pk_bf16_f32 v74, v76, v77
	v_cvt_pk_bf16_f32 v75, v78, v79
	s_nop 0
	v_permlane16_swap_b32_e32 v72, v74
	v_permlane16_swap_b32_e32 v73, v75
	global_store_dwordx4 v[86:87], v[72:75], off
	v_mov_b32_e32 v82, v234
	v_mov_b32_e32 v83, v232
	v_lshl_add_u64 v[76:77], v[212:213], 0, v[84:85]
	s_waitcnt vmcnt(3)
	v_mov_b32_e32 v72, v156
	v_mov_b32_e32 v73, v157
	v_mov_b32_e32 v74, v158
	v_mov_b32_e32 v75, v159
	v_mov_b32_e32 v79, v74
	v_mov_b32_e32 v81, v75
	s_nop 0
	v_permlane16_swap_b32_e32 v72, v79
	v_permlane16_swap_b32_e32 v73, v81
	v_lshlrev_b32_e32 v74, 16, v72
	v_and_b32_e32 v75, 0xffff0000, v72
	v_lshlrev_b32_e32 v72, 16, v73
	v_and_b32_e32 v73, 0xffff0000, v73
	v_lshlrev_b32_e32 v78, 16, v79
	v_and_b32_e32 v79, 0xffff0000, v79
	v_lshlrev_b32_e32 v80, 16, v81
	v_and_b32_e32 v81, 0xffff0000, v81
	v_pk_mul_f32 v[64:65], v[64:65], v[74:75]
	v_pk_mul_f32 v[66:67], v[66:67], v[72:73]
	v_pk_mul_f32 v[68:69], v[68:69], v[78:79]
	v_pk_mul_f32 v[70:71], v[70:71], v[80:81]
	v_cvt_pk_bf16_f32 v64, v64, v65
	v_cvt_pk_bf16_f32 v65, v66, v67
	v_cvt_pk_bf16_f32 v66, v68, v69
	v_cvt_pk_bf16_f32 v67, v70, v71
	s_nop 0
	v_permlane16_swap_b32_e32 v64, v66
	v_permlane16_swap_b32_e32 v65, v67
	global_store_dwordx4 v[76:77], v[64:67], off
	s_nop 1
	v_add_u32_e32 v66, s40, v82
	v_add_u32_e32 v64, s42, v83
	v_ashrrev_i32_e32 v67, 31, v66
	v_ashrrev_i32_e32 v65, 31, v64
	v_lshlrev_b64 v[66:67], 11, v[66:67]
	v_lshl_add_u64 v[64:65], v[66:67], 0, v[64:65]
	v_lshlrev_b64 v[64:65], 1, v[64:65]
	v_lshl_add_u64 v[66:67], v[210:211], 0, v[64:65]
	v_mov_b32_e32 v162, 0x10000
	v_mov_b32_e32 v163, 0
	global_load_dwordx4 v[144:147], v[66:67], off
	v_lshl_add_u64 v[160:161], v[66:67], 0, v[162:163]
	global_load_dwordx4 v[148:151], v[160:161], off
	v_lshl_add_u64 v[160:161], v[160:161], 0, v[162:163]
	global_load_dwordx4 v[152:155], v[160:161], off
	v_lshl_add_u64 v[160:161], v[160:161], 0, v[162:163]
	global_load_dwordx4 v[156:159], v[160:161], off
	v_lshl_add_u64 v[70:71], v[212:213], 0, v[64:65]
	v_lshl_add_u64 v[72:73], v[64:65], 0, s[28:29]
	v_lshl_add_u64 v[74:75], v[210:211], 0, v[72:73]
	s_waitcnt vmcnt(3)
; template <int EPI, int MB, int NB> ...
;     ...
;   } else if constexpr (EPI == EPI_AP) {
; #pragma unroll
;     for (int m = 0; m < MB; ++m) {
;       const size_t ob = (size_t)(brow + lrow0 + m * 16) * DM + col0;
;       u32x2 oo[2], gg[2];
;       unwiden16(*(const i32x4*)(e.sga + ob + wofs), gg[0], gg[1]);
; #pragma unroll
;       for (int n = 0; n < NB; ++n) {
;         const u32x2 g = gg[n];
;         oo[n][0] = pk_bf16(__uint_as_float(g[0] << 16) * acc[m][n][0], __uint_as_float(g[0] & 0xffff0000u) * acc[m][n][1]);
;         oo[n][1] = pk_bf16(__uint_as_float(g[1] << 16) * acc[m][n][2], __uint_as_float(g[1] & 0xffff0000u) * acc[m][n][3]);
;       }
;       *(i32x4*)(e.o16 + ob + wofs) = widen16(oo[0], oo[1]);
;     }
	v_mov_b32_e32 v66, v144
	v_mov_b32_e32 v67, v145
	v_mov_b32_e32 v68, v146
	v_mov_b32_e32 v69, v147
	v_mov_b32_e32 v77, v68
	v_mov_b32_e32 v79, v69
	s_nop 0
	v_permlane16_swap_b32_e32 v66, v77
	v_permlane16_swap_b32_e32 v67, v79
	v_lshlrev_b32_e32 v68, 16, v66
	v_and_b32_e32 v69, 0xffff0000, v66
	v_lshlrev_b32_e32 v66, 16, v67
	v_and_b32_e32 v67, 0xffff0000, v67
	v_lshlrev_b32_e32 v76, 16, v77
	v_and_b32_e32 v77, 0xffff0000, v77
	v_lshlrev_b32_e32 v78, 16, v79
	v_and_b32_e32 v79, 0xffff0000, v79
	v_pk_mul_f32 v[56:57], v[56:57], v[68:69]
	v_pk_mul_f32 v[58:59], v[58:59], v[66:67]
	v_pk_mul_f32 v[60:61], v[60:61], v[76:77]
	v_pk_mul_f32 v[62:63], v[62:63], v[78:79]
	v_cvt_pk_bf16_f32 v56, v56, v57
	v_cvt_pk_bf16_f32 v57, v58, v59
	v_cvt_pk_bf16_f32 v58, v60, v61
	v_cvt_pk_bf16_f32 v59, v62, v63
	s_nop 0
	v_permlane16_swap_b32_e32 v56, v58
	v_permlane16_swap_b32_e32 v57, v59
	global_store_dwordx4 v[70:71], v[56:59], off
	v_lshl_add_u64 v[60:61], v[64:65], 0, s[4:5]
	v_lshl_add_u64 v[62:63], v[212:213], 0, v[72:73]
	v_lshl_add_u64 v[66:67], v[210:211], 0, v[60:61]
	s_waitcnt vmcnt(3)
	v_mov_b32_e32 v56, v148
	v_mov_b32_e32 v57, v149
	v_mov_b32_e32 v58, v150
	v_mov_b32_e32 v59, v151
	v_mov_b32_e32 v69, v58
	v_mov_b32_e32 v71, v59
	s_nop 0
	v_permlane16_swap_b32_e32 v56, v69
	v_permlane16_swap_b32_e32 v57, v71
	v_lshlrev_b32_e32 v58, 16, v56
	v_and_b32_e32 v59, 0xffff0000, v56
	v_lshlrev_b32_e32 v56, 16, v57
	v_and_b32_e32 v57, 0xffff0000, v57
	v_lshlrev_b32_e32 v68, 16, v69
	v_and_b32_e32 v69, 0xffff0000, v69
	v_lshlrev_b32_e32 v70, 16, v71
	v_and_b32_e32 v71, 0xffff0000, v71
	v_pk_mul_f32 v[48:49], v[48:49], v[58:59]
	v_pk_mul_f32 v[50:51], v[50:51], v[56:57]
	v_pk_mul_f32 v[52:53], v[52:53], v[68:69]
	v_pk_mul_f32 v[54:55], v[54:55], v[70:71]
	v_cvt_pk_bf16_f32 v48, v48, v49
	v_cvt_pk_bf16_f32 v49, v50, v51
	v_cvt_pk_bf16_f32 v50, v52, v53
	v_cvt_pk_bf16_f32 v51, v54, v55
	s_nop 0
	v_permlane16_swap_b32_e32 v48, v50
	v_permlane16_swap_b32_e32 v49, v51
	global_store_dwordx4 v[62:63], v[48:51], off
	v_lshl_add_u64 v[54:55], v[212:213], 0, v[60:61]
	v_lshl_add_u64 v[52:53], v[64:65], 0, s[30:31]
	v_lshl_add_u64 v[56:57], v[210:211], 0, v[52:53]
	s_waitcnt vmcnt(3)
	v_mov_b32_e32 v48, v152
	v_mov_b32_e32 v49, v153
	v_mov_b32_e32 v50, v154
	v_mov_b32_e32 v51, v155
	v_mov_b32_e32 v59, v50
	v_mov_b32_e32 v61, v51
	s_nop 0
	v_permlane16_swap_b32_e32 v48, v59
	v_permlane16_swap_b32_e32 v49, v61
	v_lshlrev_b32_e32 v50, 16, v48
	v_and_b32_e32 v51, 0xffff0000, v48
	v_lshlrev_b32_e32 v48, 16, v49
	v_and_b32_e32 v49, 0xffff0000, v49
	v_lshlrev_b32_e32 v58, 16, v59
	v_and_b32_e32 v59, 0xffff0000, v59
	v_lshlrev_b32_e32 v60, 16, v61
	v_and_b32_e32 v61, 0xffff0000, v61
	v_pk_mul_f32 v[40:41], v[40:41], v[50:51]
	v_pk_mul_f32 v[42:43], v[42:43], v[48:49]
	v_pk_mul_f32 v[44:45], v[44:45], v[58:59]
	v_pk_mul_f32 v[46:47], v[46:47], v[60:61]
	v_cvt_pk_bf16_f32 v40, v40, v41
	v_cvt_pk_bf16_f32 v41, v42, v43
	v_cvt_pk_bf16_f32 v42, v44, v45
	v_cvt_pk_bf16_f32 v43, v46, v47
	s_nop 0
	v_permlane16_swap_b32_e32 v40, v42
	v_permlane16_swap_b32_e32 v41, v43
	global_store_dwordx4 v[54:55], v[40:43], off
	v_mov_b32_e32 v50, v234
	v_mov_b32_e32 v51, v233
	v_lshl_add_u64 v[44:45], v[212:213], 0, v[52:53]
	s_waitcnt vmcnt(3)
	v_mov_b32_e32 v40, v156
	v_mov_b32_e32 v41, v157
	v_mov_b32_e32 v42, v158
	v_mov_b32_e32 v43, v159
	v_mov_b32_e32 v47, v42
	v_mov_b32_e32 v49, v43
	s_nop 0
	v_permlane16_swap_b32_e32 v40, v47
	v_permlane16_swap_b32_e32 v41, v49
	v_lshlrev_b32_e32 v42, 16, v40
	v_and_b32_e32 v43, 0xffff0000, v40
	v_lshlrev_b32_e32 v40, 16, v41
	v_and_b32_e32 v41, 0xffff0000, v41
	v_lshlrev_b32_e32 v46, 16, v47
	v_and_b32_e32 v47, 0xffff0000, v47
	v_lshlrev_b32_e32 v48, 16, v49
	v_and_b32_e32 v49, 0xffff0000, v49
	v_pk_mul_f32 v[32:33], v[32:33], v[42:43]
	v_pk_mul_f32 v[34:35], v[34:35], v[40:41]
	v_pk_mul_f32 v[36:37], v[36:37], v[46:47]
	v_pk_mul_f32 v[38:39], v[38:39], v[48:49]
	v_cvt_pk_bf16_f32 v32, v32, v33
	v_cvt_pk_bf16_f32 v33, v34, v35
	v_cvt_pk_bf16_f32 v34, v36, v37
	v_cvt_pk_bf16_f32 v35, v38, v39
	s_nop 0
	v_permlane16_swap_b32_e32 v32, v34
	v_permlane16_swap_b32_e32 v33, v35
	global_store_dwordx4 v[44:45], v[32:35], off
	s_nop 1
	v_add_u32_e32 v34, s40, v50
	v_add_u32_e32 v32, s42, v51
	v_ashrrev_i32_e32 v35, 31, v34
	v_ashrrev_i32_e32 v33, 31, v32
	v_lshlrev_b64 v[34:35], 11, v[34:35]
	v_lshl_add_u64 v[32:33], v[34:35], 0, v[32:33]
	v_lshlrev_b64 v[32:33], 1, v[32:33]
	v_lshl_add_u64 v[34:35], v[210:211], 0, v[32:33]
	v_mov_b32_e32 v162, 0x10000
	v_mov_b32_e32 v163, 0
	global_load_dwordx4 v[144:147], v[34:35], off
	v_lshl_add_u64 v[160:161], v[34:35], 0, v[162:163]
	global_load_dwordx4 v[148:151], v[160:161], off
	v_lshl_add_u64 v[160:161], v[160:161], 0, v[162:163]
	global_load_dwordx4 v[152:155], v[160:161], off
	v_lshl_add_u64 v[160:161], v[160:161], 0, v[162:163]
	global_load_dwordx4 v[156:159], v[160:161], off
	v_lshl_add_u64 v[38:39], v[212:213], 0, v[32:33]
	v_lshl_add_u64 v[40:41], v[32:33], 0, s[28:29]
	v_lshl_add_u64 v[42:43], v[210:211], 0, v[40:41]
	s_mov_b64 s[40:41], -1
	s_waitcnt vmcnt(3)
; template <int EPI, int MB, int NB> ...
;     ...
;   } else if constexpr (EPI == EPI_AP) {
; #pragma unroll
;     for (int m = 0; m < MB; ++m) {
;       const size_t ob = (size_t)(brow + lrow0 + m * 16) * DM + col0;
;       u32x2 oo[2], gg[2];
;       unwiden16(*(const i32x4*)(e.sga + ob + wofs), gg[0], gg[1]);
; #pragma unroll
;       for (int n = 0; n < NB; ++n) {
;         const u32x2 g = gg[n];
;         oo[n][0] = pk_bf16(__uint_as_float(g[0] << 16) * acc[m][n][0], __uint_as_float(g[0] & 0xffff0000u) * acc[m][n][1]);
;         oo[n][1] = pk_bf16(__uint_as_float(g[1] << 16) * acc[m][n][2], __uint_as_float(g[1] & 0xffff0000u) * acc[m][n][3]);
;       }
;       *(i32x4*)(e.o16 + ob + wofs) = widen16(oo[0], oo[1]);
;     }
	v_mov_b32_e32 v34, v144
	v_mov_b32_e32 v35, v145
	v_mov_b32_e32 v36, v146
	v_mov_b32_e32 v37, v147
	v_mov_b32_e32 v45, v36
	v_mov_b32_e32 v47, v37
	s_nop 0
	v_permlane16_swap_b32_e32 v34, v45
	v_permlane16_swap_b32_e32 v35, v47
	v_lshlrev_b32_e32 v36, 16, v34
	v_and_b32_e32 v37, 0xffff0000, v34
	v_lshlrev_b32_e32 v34, 16, v35
	v_and_b32_e32 v35, 0xffff0000, v35
	v_lshlrev_b32_e32 v44, 16, v45
	v_and_b32_e32 v45, 0xffff0000, v45
	v_lshlrev_b32_e32 v46, 16, v47
	v_and_b32_e32 v47, 0xffff0000, v47
	v_pk_mul_f32 v[24:25], v[24:25], v[36:37]
	v_pk_mul_f32 v[26:27], v[26:27], v[34:35]
	v_pk_mul_f32 v[28:29], v[28:29], v[44:45]
	v_pk_mul_f32 v[30:31], v[30:31], v[46:47]
	v_cvt_pk_bf16_f32 v24, v24, v25
	v_cvt_pk_bf16_f32 v25, v26, v27
	v_cvt_pk_bf16_f32 v26, v28, v29
	v_cvt_pk_bf16_f32 v27, v30, v31
	s_nop 0
	v_permlane16_swap_b32_e32 v24, v26
	v_permlane16_swap_b32_e32 v25, v27
	global_store_dwordx4 v[38:39], v[24:27], off
	v_lshl_add_u64 v[28:29], v[32:33], 0, s[4:5]
	v_lshl_add_u64 v[30:31], v[212:213], 0, v[40:41]
	v_lshl_add_u64 v[34:35], v[210:211], 0, v[28:29]
	s_waitcnt vmcnt(3)
	v_mov_b32_e32 v24, v148
	v_mov_b32_e32 v25, v149
	v_mov_b32_e32 v26, v150
	v_mov_b32_e32 v27, v151
	v_mov_b32_e32 v37, v26
	v_mov_b32_e32 v39, v27
	s_nop 0
	v_permlane16_swap_b32_e32 v24, v37
	v_permlane16_swap_b32_e32 v25, v39
	v_lshlrev_b32_e32 v26, 16, v24
	v_and_b32_e32 v27, 0xffff0000, v24
	v_lshlrev_b32_e32 v24, 16, v25
	v_and_b32_e32 v25, 0xffff0000, v25
	v_lshlrev_b32_e32 v36, 16, v37
	v_and_b32_e32 v37, 0xffff0000, v37
	v_lshlrev_b32_e32 v38, 16, v39
	v_and_b32_e32 v39, 0xffff0000, v39
	v_pk_mul_f32 v[16:17], v[16:17], v[26:27]
	v_pk_mul_f32 v[18:19], v[18:19], v[24:25]
	v_pk_mul_f32 v[20:21], v[20:21], v[36:37]
	v_pk_mul_f32 v[22:23], v[22:23], v[38:39]
	v_cvt_pk_bf16_f32 v16, v16, v17
	v_cvt_pk_bf16_f32 v17, v18, v19
	v_cvt_pk_bf16_f32 v18, v20, v21
	v_cvt_pk_bf16_f32 v19, v22, v23
	s_nop 0
	v_permlane16_swap_b32_e32 v16, v18
	v_permlane16_swap_b32_e32 v17, v19
	global_store_dwordx4 v[30:31], v[16:19], off
	v_lshl_add_u64 v[22:23], v[212:213], 0, v[28:29]
	v_lshl_add_u64 v[20:21], v[32:33], 0, s[30:31]
	v_lshl_add_u64 v[24:25], v[210:211], 0, v[20:21]
	s_waitcnt vmcnt(3)
	v_mov_b32_e32 v16, v152
	v_mov_b32_e32 v17, v153
	v_mov_b32_e32 v18, v154
	v_mov_b32_e32 v19, v155
	v_mov_b32_e32 v27, v18
	v_mov_b32_e32 v29, v19
	s_nop 0
	v_permlane16_swap_b32_e32 v16, v27
	v_permlane16_swap_b32_e32 v17, v29
	v_lshlrev_b32_e32 v18, 16, v16
	v_and_b32_e32 v19, 0xffff0000, v16
	v_lshlrev_b32_e32 v16, 16, v17
	v_and_b32_e32 v17, 0xffff0000, v17
	v_lshlrev_b32_e32 v26, 16, v27
	v_and_b32_e32 v27, 0xffff0000, v27
	v_lshlrev_b32_e32 v28, 16, v29
	v_and_b32_e32 v29, 0xffff0000, v29
	v_pk_mul_f32 v[8:9], v[8:9], v[18:19]
	v_pk_mul_f32 v[10:11], v[10:11], v[16:17]
	v_pk_mul_f32 v[12:13], v[12:13], v[26:27]
	v_pk_mul_f32 v[14:15], v[14:15], v[28:29]
	v_cvt_pk_bf16_f32 v8, v8, v9
	v_cvt_pk_bf16_f32 v9, v10, v11
	v_cvt_pk_bf16_f32 v10, v12, v13
	v_cvt_pk_bf16_f32 v11, v14, v15
	s_nop 0
	v_permlane16_swap_b32_e32 v8, v10
	v_permlane16_swap_b32_e32 v9, v11
	global_store_dwordx4 v[22:23], v[8:11], off
	v_lshl_add_u64 v[12:13], v[212:213], 0, v[20:21]
	s_waitcnt vmcnt(3)
	v_mov_b32_e32 v8, v156
	v_mov_b32_e32 v9, v157
	v_mov_b32_e32 v10, v158
	v_mov_b32_e32 v11, v159
	v_mov_b32_e32 v15, v10
	v_mov_b32_e32 v17, v11
	s_nop 0
	v_permlane16_swap_b32_e32 v8, v15
	v_permlane16_swap_b32_e32 v9, v17
	v_lshlrev_b32_e32 v10, 16, v8
	v_and_b32_e32 v11, 0xffff0000, v8
	v_lshlrev_b32_e32 v8, 16, v9
	v_and_b32_e32 v9, 0xffff0000, v9
	v_lshlrev_b32_e32 v14, 16, v15
	v_and_b32_e32 v15, 0xffff0000, v15
	v_lshlrev_b32_e32 v16, 16, v17
	v_and_b32_e32 v17, 0xffff0000, v17
	v_pk_mul_f32 v[0:1], v[0:1], v[10:11]
	v_pk_mul_f32 v[2:3], v[2:3], v[8:9]
	v_pk_mul_f32 v[4:5], v[4:5], v[14:15]
	v_pk_mul_f32 v[6:7], v[6:7], v[16:17]
	v_cvt_pk_bf16_f32 v0, v0, v1
	v_cvt_pk_bf16_f32 v1, v2, v3
	v_cvt_pk_bf16_f32 v2, v4, v5
	v_cvt_pk_bf16_f32 v3, v6, v7
	s_nop 0
	v_permlane16_swap_b32_e32 v0, v2
	v_permlane16_swap_b32_e32 v1, v3
	global_store_dwordx4 v[12:13], v[0:3], off
	s_cbranch_vccz .LBB0_361
